# Z_H2_E1_D
# speedup vs baseline: 1.0093x; 1.0053x over previous
;     __host__ __device__ bool next(int i, Unit& u) const {
;     ...
;         int wgid = (int)L; { const int q = nwg / NXCD, r = nwg % NXCD, xcd = wgid % NXCD, off = wgid / NXCD; wgid = (xcd < r ? xcd * (q + 1) : r * (q + 1) + (xcd - r) * q) + off; }
;         const int nig = wgm * nN, gid = wgid / nig, fm = gid * wgm, gsz = (nM - fm) < wgm ? (nM - fm) : wgm;
;         u.pm = fm + ((wgid % nig) % gsz); u.pn = (wgid % nig) / gsz; u.sub = 0; return true;
.LBB0_250:
	s_ashr_i32 s0, s7, 3
	s_add_i32 s0, s16, s0
	s_mul_hi_i32 s1, s0, 0x51eb851f
	s_lshr_b32 s7, s1, 31
	s_ashr_i32 s1, s1, 6
	s_add_i32 s1, s1, s7
	s_lshl_b32 s7, s1, 2
	s_sub_i32 s9, 0x81, s7
	s_min_i32 s9, s9, 4
	s_mulk_i32 s1, 0xc8
	s_sub_i32 s1, s0, s1
	s_cmp_eq_u32 s9, 4
	s_cselect_b32 s16, 2, 0
	s_lshr_b32 s0, s1, s16
	s_mul_i32 s9, s0, s9
	s_sub_i32 s1, s1, s9
	s_add_i32 s86, s7, s1

;     __host__ __device__ bool next(int i, Unit& u) const {
;     ...
;         int wgid = (int)L; { const int q = nwg / NXCD, r = nwg % NXCD, xcd = wgid % NXCD, off = wgid / NXCD; wgid = (xcd < r ? xcd * (q + 1) : r * (q + 1) + (xcd - r) * q) + off; }
;         const int nig = wgm * nN, gid = wgid / nig, fm = gid * wgm, gsz = (nM - fm) < wgm ? (nM - fm) : wgm;
;         u.pm = fm + ((wgid % nig) % gsz); u.pn = (wgid % nig) / gsz; u.sub = 0; return true;
.LBB0_990:
	s_ashr_i32 s22, s24, 3
	s_add_i32 s22, s28, s22
	s_mul_hi_i32 s23, s22, 0x2e8ba2e9
	s_lshr_b32 s24, s23, 31
	s_ashr_i32 s23, s23, 5
	s_add_i32 s23, s23, s24
	s_lshl_b32 s24, s23, 2
	s_sub_i32 s25, 0x81, s24
	s_min_i32 s25, s25, 4
	s_mulk_i32 s23, 0xb0
	s_sub_i32 s23, s22, s23
	s_cmp_eq_u32 s25, 4
	s_cselect_b32 s28, 2, 0
	s_lshr_b32 s22, s23, s28
	s_mul_i32 s25, s22, s25
	s_sub_i32 s23, s23, s25
	s_add_i32 s24, s24, s23
